# P2 sample-row pooling loop: window rows touched by loads issued together before the serial window loop
# speedup vs baseline: 1.0143x; 1.0114x over previous
; DEV float bflo(unsigned u) { return __uint_as_float(u << 16); }
; DEV float bfhi(unsigned u) { return __uint_as_float(u & 0xffff0000u); }
; __global__ void __launch_bounds__(512) hymba_fwd(Params p) {
;     ...
;         for (int i = TP * 128 + bid * 512 + tid; i < TT * 128; i += G * 512) {
;             const int row = i >> 7, c8 = (i & 127) * 8, g = c8 >> 8, win = 2 << g;
;             float acc[8] = {0.f, 0.f, 0.f, 0.f, 0.f, 0.f, 0.f, 0.f}, self[8];
;             const int tloc = (row - TP) & 3;
;             for (int k = 0; k < win; ++k) {
;                 const int tt = tloc - k;
;                 if (tt >= 0) {
;                     const uint4 u = *(const uint4*)(proj + (size_t)(row - k) * NPJ + C_U + c8);
;                     const float f[8] = {bflo(u.x), bfhi(u.x), bflo(u.y), bfhi(u.y), bflo(u.z), bfhi(u.z), bflo(u.w), bfhi(u.w)};
; #pragma unroll
;                     for (int e = 0; e < 8; ++e) { acc[e] += f[e]; if (k == 0) self[e] = f[e]; }
;                 } else {
;                     const float* sp = p.in[7] + ((size_t)((row - TP) >> 2) * 15 + (15 + tt)) * 1024 + c8;
;                     const f32x4 s0 = *(const f32x4*)sp, s1 = *(const f32x4*)(sp + 4);
;                     acc[0] += s0[0]; acc[1] += s0[1]; acc[2] += s0[2]; acc[3] += s0[3]; acc[4] += s1[0]; acc[5] += s1[1]; acc[6] += s1[2]; acc[7] += s1[3];
;                 }
;             }
.LBB0_749:
	v_lshlrev_b32_e32 v6, 3, v23
	v_and_b32_e32 v24, 0x3f8, v6
	v_ashrrev_i32_e32 v22, 7, v23
	v_lshlrev_b32_e32 v20, 2, v24
	s_waitcnt lgkmcnt(0)
	v_lshl_add_u64 v[26:27], s[6:7], 0, v[20:21]
	v_mad_i64_i32 v[2:3], s[12:13], v22, s20, v[172:173]
	v_lshlrev_b32_e32 v20, 1, v24
	v_lshl_add_u64 v[2:3], v[2:3], 0, v[20:21]
	v_add_co_u32_e32 v2, vcc, s21, v2
	v_bfe_u32 v9, v6, 8, 2
	s_nop 0
	v_addc_co_u32_e32 v3, vcc, 0, v3, vcc
	global_load_dwordx4 v[2:5], v[2:3], off
	v_add_u32_e32 v10, 0xffffe000, v22
	v_lshlrev_b32_e32 v8, 1, v25
	v_mad_i64_i32 v[6:7], s[16:17], v22, s20, 0
	v_lshlrev_b32_e64 v40, v9, 2
	v_lshrrev_b32_e32 v9, 2, v10
	v_and_or_b32 v6, v8, s22, v6
	v_mul_i32_i24_e32 v36, 15, v9
	s_mov_b64 s[12:13], 0
	v_and_b32_e32 v41, 3, v22
	v_add_u32_e32 v42, -1, v40
	v_lshl_add_u64 v[38:39], v[18:19], 0, v[6:7]
	v_ashrrev_i32_e32 v37, 31, v36
	s_mov_b32 s25, 0
	v_lshlrev_b64 v[52:53], 12, v[36:37]
	v_lshl_add_u64 v[52:53], v[26:27], 0, v[52:53]
	s_mov_b64 s[34:35], 0x1000
	global_load_dwordx4 v[48:51], v[52:53], off
	v_lshl_add_u64 v[52:53], v[52:53], 0, s[34:35]
	global_load_dwordx4 v[48:51], v[52:53], off
	v_lshl_add_u64 v[52:53], v[52:53], 0, s[34:35]
	global_load_dwordx4 v[48:51], v[52:53], off
	v_lshl_add_u64 v[52:53], v[52:53], 0, s[34:35]
	global_load_dwordx4 v[48:51], v[52:53], off
	v_lshl_add_u64 v[52:53], v[52:53], 0, s[34:35]
	global_load_dwordx4 v[48:51], v[52:53], off
	v_lshl_add_u64 v[52:53], v[52:53], 0, s[34:35]
	global_load_dwordx4 v[48:51], v[52:53], off
	v_lshl_add_u64 v[52:53], v[52:53], 0, s[34:35]
	global_load_dwordx4 v[48:51], v[52:53], off
	v_lshl_add_u64 v[52:53], v[52:53], 0, s[34:35]
	global_load_dwordx4 v[48:51], v[52:53], off
	v_lshl_add_u64 v[52:53], v[52:53], 0, s[34:35]
	global_load_dwordx4 v[48:51], v[52:53], off
	v_lshl_add_u64 v[52:53], v[52:53], 0, s[34:35]
	global_load_dwordx4 v[48:51], v[52:53], off
	v_lshl_add_u64 v[52:53], v[52:53], 0, s[34:35]
	global_load_dwordx4 v[48:51], v[52:53], off
	v_lshl_add_u64 v[52:53], v[52:53], 0, s[34:35]
	global_load_dwordx4 v[48:51], v[52:53], off
	v_lshl_add_u64 v[52:53], v[52:53], 0, s[34:35]
	global_load_dwordx4 v[48:51], v[52:53], off
	v_lshl_add_u64 v[52:53], v[52:53], 0, s[34:35]
	global_load_dwordx4 v[48:51], v[52:53], off
	v_lshl_add_u64 v[52:53], v[52:53], 0, s[34:35]
	global_load_dwordx4 v[48:51], v[52:53], off
	global_load_dwordx4 v[48:51], v[38:39], off
	v_lshl_add_u64 v[54:55], v[38:39], 0, s[10:11]
	global_load_dwordx4 v[48:51], v[54:55], off
	v_lshl_add_u64 v[54:55], v[54:55], 0, s[10:11]
	global_load_dwordx4 v[48:51], v[54:55], off
	s_waitcnt vmcnt(0)
	v_lshlrev_b32_e32 v34, 16, v2
	v_and_b32_e32 v35, 0xffff0000, v2
	v_lshlrev_b32_e32 v32, 16, v3
	v_and_b32_e32 v33, 0xffff0000, v3
	v_lshlrev_b32_e32 v30, 16, v4
	v_and_b32_e32 v31, 0xffff0000, v4
	v_lshlrev_b32_e32 v28, 16, v5
	v_and_b32_e32 v29, 0xffff0000, v5
	v_pk_add_f32 v[16:17], v[28:29], 0 op_sel_hi:[1,0]
	v_pk_add_f32 v[14:15], v[30:31], 0 op_sel_hi:[1,0]
	v_pk_add_f32 v[12:13], v[32:33], 0 op_sel_hi:[1,0]
	v_pk_add_f32 v[10:11], v[34:35], 0 op_sel_hi:[1,0]
	s_branch .LBB0_751
